# odd attention softmax: score scale folded into exp argument via fma, row max taken on raw scores (f32, same math order otherwise)
# speedup vs baseline: 1.0131x; 1.0025x over previous
.LBB0_426:
	s_mov_b32 s32, 0x3e38aa3b
	v_add_u32_e32 v112, v129, v140
	s_barrier
	s_waitcnt vmcnt(0)
	ds_write_b128 v112, v[24:27]
	v_add_u32_e32 v112, v141, v142
	ds_write_b128 v112, v[28:31]
	v_add_u32_e32 v112, v143, v144
	s_add_i32 s27, s28, 1
	ds_write_b128 v112, v[40:43]
	v_add_u32_e32 v112, v145, v146
	s_cmp_ge_u32 s27, s3
	ds_write_b128 v112, v[44:47]
	ds_write_b128 v147, v[32:35] offset:18432
	ds_write_b128 v148, v[36:39] offset:18432
	ds_write_b128 v149, v[16:19] offset:18432
	ds_write_b128 v150, v[20:23] offset:18432
	s_waitcnt lgkmcnt(0)
	s_barrier
	s_cbranch_scc1 .LBB0_430
	s_cmp_lt_u32 s27, s2
	s_mov_b32 s29, s27
	s_mov_b64 s[18:19], s[10:11]
	s_mov_b64 s[22:23], s[6:7]
	s_mov_b64 s[20:21], s[8:9]
	s_cbranch_scc1 .LBB0_429
	s_add_i32 s29, s25, s28
	s_mov_b64 s[18:19], 0xc00
	s_mov_b64 s[22:23], s[14:15]
	s_mov_b64 s[20:21], s[16:17]

.LBB0_430:
	ds_read_b128 v[158:161], v153 offset:4608
	ds_read_b128 v[162:165], v153 offset:4672
	ds_read_b128 v[112:115], v153
	ds_read_b128 v[116:119], v153 offset:64
	s_waitcnt lgkmcnt(3)
	v_mfma_f32_16x16x32_bf16 v[158:161], v[158:161], v[0:3], 0
	ds_read_b128 v[168:171], v153 offset:9280
	ds_read_b128 v[174:177], v153 offset:13888
	s_waitcnt lgkmcnt(4)
	v_mfma_f32_16x16x32_bf16 v[160:163], v[162:165], v[4:7], v[158:161]
	ds_read_b128 v[164:167], v153 offset:9216
	s_waitcnt lgkmcnt(0)
	v_mfma_f32_16x16x32_bf16 v[164:167], v[164:167], v[0:3], 0
	s_nop 4
	s_nop 0
	v_mfma_f32_16x16x32_bf16 v[166:169], v[168:171], v[4:7], v[164:167]
	ds_read_b128 v[170:173], v153 offset:13824
	v_mfma_f32_16x16x32_bf16 v[112:115], v[112:115], v[0:3], 0
	s_nop 0
	s_nop 0
	s_nop 3
	s_nop 0
	s_nop 0
	v_mfma_f32_16x16x32_bf16 v[114:117], v[116:119], v[4:7], v[112:115]
	s_nop 0
	s_waitcnt lgkmcnt(0)
	v_mfma_f32_16x16x32_bf16 v[170:173], v[170:173], v[0:3], 0
	v_mfma_f32_16x16x32_bf16 v[170:173], v[174:177], v[4:7], v[170:173]
	s_nop 7
	s_nop 1
	v_max3_f32 v194, v114, s30, v115
	v_max3_f32 v194, v194, v116, v117
	v_max3_f32 v194, v194, v160, v161
	v_max3_f32 v194, v194, v162, v163
	v_max3_f32 v194, v194, v166, v167
	v_max3_f32 v194, v194, v168, v169
	v_max3_f32 v194, v194, v170, v171
	v_max3_f32 v194, v194, v172, v173
	v_mov_b32_e32 v195, v194
	s_nop 1
	v_permlane16_swap_b32_e32 v194, v195
	v_max_f32_e32 v195, v195, v195
	v_max_f32_e32 v194, v194, v194
	v_max_f32_e32 v194, v194, v195
	v_mov_b32_e32 v195, v194
	s_nop 1
	v_permlane32_swap_b32_e32 v194, v195
	v_max_f32_e32 v194, v194, v195
	v_mul_f32_e32 v194, 0x3e38aa3b, v194
	v_max_f32_e32 v165, v155, v194
	v_fma_f32 v163, v163, s32, -v165
	v_fma_f32 v164, v162, s32, -v165
	v_fma_f32 v159, v166, s32, -v165
	v_fma_f32 v158, v167, s32, -v165
	v_fma_f32 v162, v168, s32, -v165
	v_fma_f32 v113, v114, s32, -v165
	v_fma_f32 v112, v115, s32, -v165
	v_fma_f32 v116, v116, s32, -v165
	v_fma_f32 v114, v117, s32, -v165
	v_fma_f32 v115, v160, s32, -v165
	v_fma_f32 v160, v161, s32, -v165
	v_fma_f32 v161, v169, s32, -v165
	v_fma_f32 v157, v170, s32, -v165
	v_fma_f32 v118, v171, s32, -v165
	v_fma_f32 v119, v172, s32, -v165
	v_fma_f32 v117, v173, s32, -v165
	v_cmp_gt_f32_e32 vcc, v165, v155
	s_cbranch_vccz .LBB0_432
	v_sub_f32_e32 v155, v155, v165
	v_exp_f32_e32 v166, v155
	v_mov_b32_e32 v155, v165
	v_mul_f32_e32 v131, v131, v166
	v_pk_mul_f32 v[98:99], v[98:99], v[166:167] op_sel_hi:[1,0]
	v_pk_mul_f32 v[96:97], v[96:97], v[166:167] op_sel_hi:[1,0]
	v_pk_mul_f32 v[102:103], v[102:103], v[166:167] op_sel_hi:[1,0]
	v_pk_mul_f32 v[100:101], v[100:101], v[166:167] op_sel_hi:[1,0]
	v_pk_mul_f32 v[70:71], v[70:71], v[166:167] op_sel_hi:[1,0]
	v_pk_mul_f32 v[68:69], v[68:69], v[166:167] op_sel_hi:[1,0]
	v_pk_mul_f32 v[54:55], v[54:55], v[166:167] op_sel_hi:[1,0]
	v_pk_mul_f32 v[52:53], v[52:53], v[166:167] op_sel_hi:[1,0]
	v_pk_mul_f32 v[82:83], v[82:83], v[166:167] op_sel_hi:[1,0]
	v_pk_mul_f32 v[80:81], v[80:81], v[166:167] op_sel_hi:[1,0]
	v_pk_mul_f32 v[86:87], v[86:87], v[166:167] op_sel_hi:[1,0]
	v_pk_mul_f32 v[84:85], v[84:85], v[166:167] op_sel_hi:[1,0]
	v_pk_mul_f32 v[78:79], v[78:79], v[166:167] op_sel_hi:[1,0]
	v_pk_mul_f32 v[76:77], v[76:77], v[166:167] op_sel_hi:[1,0]
	v_pk_mul_f32 v[110:111], v[110:111], v[166:167] op_sel_hi:[1,0]
	v_pk_mul_f32 v[108:109], v[108:109], v[166:167] op_sel_hi:[1,0]
.LBB0_432:
	v_exp_f32_e32 v167, v112
	v_exp_f32_e32 v168, v116
	v_exp_f32_e32 v169, v114
	v_exp_f32_e32 v170, v115
	v_exp_f32_e32 v171, v160
	v_exp_f32_e32 v172, v164
	v_exp_f32_e32 v166, v113
	v_exp_f32_e32 v173, v163
	v_exp_f32_e32 v174, v159
	v_exp_f32_e32 v175, v158
	v_exp_f32_e32 v176, v162
	v_exp_f32_e32 v177, v161
	v_exp_f32_e32 v178, v157
	v_exp_f32_e32 v179, v118
	v_exp_f32_e32 v180, v119
	v_exp_f32_e32 v181, v117
	s_nop 0
	v_cvt_pk_bf16_f32 v217, v168, v169
	v_cvt_pk_bf16_f32 v218, v170, v171
	v_cvt_pk_bf16_f32 v216, v166, v167
	v_cvt_pk_bf16_f32 v219, v172, v173
	v_cvt_pk_bf16_f32 v220, v174, v175
	v_cvt_pk_bf16_f32 v221, v176, v177
	v_cvt_pk_bf16_f32 v222, v178, v179
	v_cvt_pk_bf16_f32 v223, v180, v181
	ds_read_b128 v[112:115], v153 offset:128
	ds_read_b128 v[116:119], v153 offset:192
	s_waitcnt lgkmcnt(1)
	v_mfma_f32_16x16x32_bf16 v[112:115], v[112:115], v[8:11], 0
	ds_read_b128 v[158:161], v153 offset:4736
	ds_read_b128 v[162:165], v153 offset:9344
	ds_read_b128 v[182:185], v153 offset:13952
	s_waitcnt lgkmcnt(3)
	v_mfma_f32_16x16x32_bf16 v[112:115], v[116:119], v[12:15], v[112:115]
	ds_read_b128 v[116:119], v153 offset:4800
	s_waitcnt lgkmcnt(3)
	v_mfma_f32_16x16x32_bf16 v[158:161], v[158:161], v[8:11], 0
	s_waitcnt lgkmcnt(0)
	v_mfma_f32_16x16x32_bf16 v[116:119], v[116:119], v[12:15], v[158:161]
	s_nop 5
	ds_read_b128 v[158:161], v153 offset:9408
	v_mfma_f32_16x16x32_bf16 v[162:165], v[162:165], v[8:11], 0
	s_waitcnt lgkmcnt(0)
	v_mfma_f32_16x16x32_bf16 v[186:189], v[158:161], v[12:15], v[162:165]
	ds_read_b128 v[158:161], v153 offset:14016
	s_nop 6
	s_nop 0
	v_mfma_f32_16x16x32_bf16 v[162:165], v[182:185], v[8:11], 0
	s_waitcnt lgkmcnt(0)
	v_mfma_f32_16x16x32_bf16 v[182:185], v[158:161], v[12:15], v[162:165]
	s_nop 7
	s_nop 1
	v_max3_f32 v194, v112, s30, v113
	v_max3_f32 v194, v194, v114, v115
	v_max3_f32 v194, v194, v116, v117
	v_max3_f32 v194, v194, v118, v119
	v_max3_f32 v194, v194, v186, v187
	v_max3_f32 v194, v194, v188, v189
	v_max3_f32 v194, v194, v182, v183
	v_max3_f32 v194, v194, v184, v185
	v_mov_b32_e32 v195, v194
	s_nop 1
	v_permlane16_swap_b32_e32 v194, v195
	v_max_f32_e32 v195, v195, v195
	v_max_f32_e32 v194, v194, v194
	v_max_f32_e32 v194, v194, v195
	v_mov_b32_e32 v195, v194
	s_nop 1
	v_permlane32_swap_b32_e32 v194, v195
	v_max_f32_e32 v194, v194, v195
	v_mul_f32_e32 v194, 0x3e38aa3b, v194
	v_max_f32_e32 v215, v156, v194
	v_fma_f32 v157, v186, s32, -v215
	v_fma_f32 v161, v116, s32, -v215
	v_fma_f32 v159, v117, s32, -v215
	v_fma_f32 v165, v112, s32, -v215
	v_fma_f32 v163, v113, s32, -v215
	v_fma_f32 v164, v114, s32, -v215
	v_fma_f32 v162, v115, s32, -v215
	v_fma_f32 v160, v118, s32, -v215
	v_fma_f32 v158, v119, s32, -v215
	v_fma_f32 v118, v187, s32, -v215
	v_fma_f32 v119, v188, s32, -v215
	v_fma_f32 v117, v189, s32, -v215
	v_fma_f32 v115, v182, s32, -v215
	v_fma_f32 v113, v183, s32, -v215
	v_fma_f32 v114, v184, s32, -v215
	v_fma_f32 v112, v185, s32, -v215
	v_mov_b32_e32 v116, v215
	v_cmp_gt_f32_e32 vcc, v116, v156
	s_cbranch_vccz .LBB0_434
	v_sub_f32_e32 v156, v156, v116
	v_exp_f32_e32 v156, v156
	s_nop 0
	v_mul_f32_e32 v121, v121, v156
	v_pk_mul_f32 v[94:95], v[94:95], v[156:157] op_sel_hi:[1,0]
	v_pk_mul_f32 v[92:93], v[92:93], v[156:157] op_sel_hi:[1,0]
	v_pk_mul_f32 v[90:91], v[90:91], v[156:157] op_sel_hi:[1,0]
	v_pk_mul_f32 v[88:89], v[88:89], v[156:157] op_sel_hi:[1,0]
	v_pk_mul_f32 v[58:59], v[58:59], v[156:157] op_sel_hi:[1,0]
	v_pk_mul_f32 v[56:57], v[56:57], v[156:157] op_sel_hi:[1,0]
	v_pk_mul_f32 v[50:51], v[50:51], v[156:157] op_sel_hi:[1,0]
	v_pk_mul_f32 v[48:49], v[48:49], v[156:157] op_sel_hi:[1,0]
	v_pk_mul_f32 v[66:67], v[66:67], v[156:157] op_sel_hi:[1,0]
	v_pk_mul_f32 v[64:65], v[64:65], v[156:157] op_sel_hi:[1,0]
	v_pk_mul_f32 v[74:75], v[74:75], v[156:157] op_sel_hi:[1,0]
	v_pk_mul_f32 v[72:73], v[72:73], v[156:157] op_sel_hi:[1,0]
	v_pk_mul_f32 v[62:63], v[62:63], v[156:157] op_sel_hi:[1,0]
	v_pk_mul_f32 v[60:61], v[60:61], v[156:157] op_sel_hi:[1,0]
	v_pk_mul_f32 v[106:107], v[106:107], v[156:157] op_sel_hi:[1,0]
	v_pk_mul_f32 v[104:105], v[104:105], v[156:157] op_sel_hi:[1,0]
	v_mov_b32_e32 v156, v116
.LBB0_434:
	v_add_f32_e32 v166, v166, v167
	v_add_f32_e32 v167, v168, v169
	v_add_f32_e32 v166, v166, v167
	v_add_f32_e32 v167, v170, v171
	v_add_f32_e32 v168, v172, v173
	v_add_f32_e32 v166, 0, v166
	v_add_f32_e32 v167, v167, v168
	v_add_f32_e32 v166, v167, v166
	v_add_f32_e32 v167, v174, v175
	v_add_f32_e32 v168, v176, v177
	v_add_f32_e32 v167, v167, v168
	v_add_f32_e32 v166, v167, v166
	v_add_f32_e32 v167, v178, v179
	v_add_f32_e32 v168, v180, v181
	v_add_f32_e32 v167, v167, v168
	v_add_f32_e32 v166, v167, v166
	v_exp_f32_e32 v168, v163
	v_add_f32_e32 v131, v166, v131
	v_exp_f32_e32 v166, v165
	v_exp_f32_e32 v167, v164
	v_exp_f32_e32 v169, v162
	v_cvt_pk_bf16_f32 v224, v166, v168
	v_pk_add_f32 v[162:163], v[166:167], v[168:169]
	v_exp_f32_e32 v168, v159
	v_cvt_pk_bf16_f32 v225, v167, v169
	v_exp_f32_e32 v166, v161
	v_exp_f32_e32 v167, v160
	v_exp_f32_e32 v169, v158
	s_nop 0
	v_pk_add_f32 v[158:159], v[166:167], v[168:169]
	v_pk_add_f32 v[158:159], v[158:159], v[158:159] op_sel_hi:[0,1]
	v_exp_f32_e32 v157, v157
	v_exp_f32_e32 v118, v118
	v_exp_f32_e32 v158, v119
	v_exp_f32_e32 v117, v117
	v_cvt_pk_bf16_f32 v226, v166, v168
	v_cvt_pk_bf16_f32 v227, v167, v169
	v_add_f32_e32 v162, v162, v163
	v_exp_f32_e32 v160, v113
	v_add_f32_e32 v163, 0, v162
	v_add_f32_e32 v119, v157, v118
	v_add_f32_e32 v161, v158, v117
	v_cvt_pk_bf16_f32 v230, v157, v118
	v_cvt_pk_bf16_f32 v231, v158, v117
	v_exp_f32_e32 v118, v115
	v_exp_f32_e32 v158, v114
	v_exp_f32_e32 v162, v112
	s_cmp_lg_u32 s26, s27
	v_pk_add_f32 v[112:113], v[118:119], v[160:161]
	v_pk_add_f32 v[114:115], v[158:159], v[162:163]
	s_nop 0
	v_pk_add_f32 v[112:113], v[112:113], v[114:115]
	s_nop 0
	v_add_f32_e32 v114, v112, v113
	v_cvt_pk_bf16_f32 v232, v118, v160
	v_cvt_pk_bf16_f32 v233, v158, v162
	v_add_f32_e32 v121, v114, v121
	v_bfe_u32 v214, v228, 4, 2
	v_mul_u32_u24_e32 v214, 0x440, v214
	v_sub_u32_e32 v214, v152, v214
	ds_read_b64_tr_b16 v[198:199], v214 offset:18432
	ds_read_b64_tr_b16 v[200:201], v214 offset:22784
	ds_read_b64_tr_b16 v[202:203], v214 offset:18464
	ds_read_b64_tr_b16 v[204:205], v214 offset:22816
	ds_read_b64_tr_b16 v[206:207], v214 offset:18496
	ds_read_b64_tr_b16 v[208:209], v214 offset:22848
	ds_read_b64_tr_b16 v[210:211], v214 offset:18528
	ds_read_b64_tr_b16 v[212:213], v214 offset:22880
	s_waitcnt lgkmcnt(6)
	v_mfma_f32_16x16x32_bf16 v[96:99], v[198:201], v[216:219], v[96:99]
	v_mfma_f32_16x16x32_bf16 v[92:95], v[198:201], v[224:227], v[92:95]
	ds_read_b64_tr_b16 v[198:199], v214 offset:18560
	ds_read_b64_tr_b16 v[200:201], v214 offset:22912
	s_waitcnt lgkmcnt(6)
	v_mfma_f32_16x16x32_bf16 v[100:103], v[202:205], v[216:219], v[100:103]
	v_mfma_f32_16x16x32_bf16 v[88:91], v[202:205], v[224:227], v[88:91]
	ds_read_b64_tr_b16 v[202:203], v214 offset:18592
	ds_read_b64_tr_b16 v[204:205], v214 offset:22944
	s_waitcnt lgkmcnt(6)
	v_mfma_f32_16x16x32_bf16 v[68:71], v[206:209], v[216:219], v[68:71]
	v_mfma_f32_16x16x32_bf16 v[56:59], v[206:209], v[224:227], v[56:59]
	ds_read_b64_tr_b16 v[206:207], v214 offset:18624
	ds_read_b64_tr_b16 v[208:209], v214 offset:22976
	s_waitcnt lgkmcnt(6)
	v_mfma_f32_16x16x32_bf16 v[52:55], v[210:213], v[216:219], v[52:55]
	v_mfma_f32_16x16x32_bf16 v[48:51], v[210:213], v[224:227], v[48:51]
	ds_read_b64_tr_b16 v[210:211], v214 offset:18656
	ds_read_b64_tr_b16 v[212:213], v214 offset:23008
	s_waitcnt lgkmcnt(6)
	v_mfma_f32_16x16x32_bf16 v[80:83], v[198:201], v[216:219], v[80:83]
	v_mfma_f32_16x16x32_bf16 v[64:67], v[198:201], v[224:227], v[64:67]
	ds_read_b64_tr_b16 v[198:199], v214 offset:27136
	ds_read_b64_tr_b16 v[200:201], v214 offset:31488
	s_waitcnt lgkmcnt(6)
	v_mfma_f32_16x16x32_bf16 v[84:87], v[202:205], v[216:219], v[84:87]
	v_mfma_f32_16x16x32_bf16 v[72:75], v[202:205], v[224:227], v[72:75]
	ds_read_b64_tr_b16 v[202:203], v214 offset:27168
	ds_read_b64_tr_b16 v[204:205], v214 offset:31520
	s_waitcnt lgkmcnt(6)
	v_mfma_f32_16x16x32_bf16 v[76:79], v[206:209], v[216:219], v[76:79]
	v_mfma_f32_16x16x32_bf16 v[60:63], v[206:209], v[224:227], v[60:63]
	ds_read_b64_tr_b16 v[206:207], v214 offset:27200
	ds_read_b64_tr_b16 v[208:209], v214 offset:31552
	s_waitcnt lgkmcnt(6)
	v_mfma_f32_16x16x32_bf16 v[108:111], v[210:213], v[216:219], v[108:111]
	v_mfma_f32_16x16x32_bf16 v[104:107], v[210:213], v[224:227], v[104:107]
	ds_read_b64_tr_b16 v[210:211], v214 offset:27232
	ds_read_b64_tr_b16 v[212:213], v214 offset:31584
	s_waitcnt lgkmcnt(6)
	v_mfma_f32_16x16x32_bf16 v[96:99], v[198:201], v[220:223], v[96:99]
	v_mfma_f32_16x16x32_bf16 v[92:95], v[198:201], v[230:233], v[92:95]
	ds_read_b64_tr_b16 v[198:199], v214 offset:27264
	ds_read_b64_tr_b16 v[200:201], v214 offset:31616
	s_waitcnt lgkmcnt(6)
	v_mfma_f32_16x16x32_bf16 v[100:103], v[202:205], v[220:223], v[100:103]
	v_mfma_f32_16x16x32_bf16 v[88:91], v[202:205], v[230:233], v[88:91]
	ds_read_b64_tr_b16 v[202:203], v214 offset:27296
	ds_read_b64_tr_b16 v[204:205], v214 offset:31648
	s_waitcnt lgkmcnt(6)
	v_mfma_f32_16x16x32_bf16 v[68:71], v[206:209], v[220:223], v[68:71]
	v_mfma_f32_16x16x32_bf16 v[56:59], v[206:209], v[230:233], v[56:59]
	ds_read_b64_tr_b16 v[206:207], v214 offset:27328
	ds_read_b64_tr_b16 v[208:209], v214 offset:31680
	s_waitcnt lgkmcnt(6)
	v_mfma_f32_16x16x32_bf16 v[52:55], v[210:213], v[220:223], v[52:55]
	v_mfma_f32_16x16x32_bf16 v[48:51], v[210:213], v[230:233], v[48:51]
	ds_read_b64_tr_b16 v[210:211], v214 offset:27360
	ds_read_b64_tr_b16 v[212:213], v214 offset:31712
	s_waitcnt lgkmcnt(6)
	v_mfma_f32_16x16x32_bf16 v[80:83], v[198:201], v[220:223], v[80:83]
	v_mfma_f32_16x16x32_bf16 v[64:67], v[198:201], v[230:233], v[64:67]
	s_waitcnt lgkmcnt(4)
	v_mfma_f32_16x16x32_bf16 v[84:87], v[202:205], v[220:223], v[84:87]
	v_mfma_f32_16x16x32_bf16 v[72:75], v[202:205], v[230:233], v[72:75]
	s_waitcnt lgkmcnt(2)
	v_mfma_f32_16x16x32_bf16 v[76:79], v[206:209], v[220:223], v[76:79]
	v_mfma_f32_16x16x32_bf16 v[60:63], v[206:209], v[230:233], v[60:63]
	s_waitcnt lgkmcnt(0)
	v_mfma_f32_16x16x32_bf16 v[108:111], v[210:213], v[220:223], v[108:111]
	v_mfma_f32_16x16x32_bf16 v[104:107], v[210:213], v[230:233], v[104:107]
	s_cbranch_scc0 .LBB0_419
	s_mov_b32 s28, s27
	s_branch .LBB0_426
